# attention: S - m as 16 packed f32 adds instead of 32 scalar subs
# baseline (speedup 1.0000x reference)
.LBB0_203:
	v_pk_add_f32 v[102:103], v[102:103], v[234:235] op_sel_hi:[1,0] neg_lo:[0,1] neg_hi:[0,1]
	v_pk_add_f32 v[100:101], v[100:101], v[234:235] op_sel_hi:[1,0] neg_lo:[0,1] neg_hi:[0,1]
	v_pk_add_f32 v[98:99], v[98:99], v[234:235] op_sel_hi:[1,0] neg_lo:[0,1] neg_hi:[0,1]
	v_pk_add_f32 v[96:97], v[96:97], v[234:235] op_sel_hi:[1,0] neg_lo:[0,1] neg_hi:[0,1]
	v_pk_add_f32 v[118:119], v[118:119], v[234:235] op_sel_hi:[1,0] neg_lo:[0,1] neg_hi:[0,1]
	v_pk_add_f32 v[116:117], v[116:117], v[234:235] op_sel_hi:[1,0] neg_lo:[0,1] neg_hi:[0,1]
	v_pk_add_f32 v[114:115], v[114:115], v[234:235] op_sel_hi:[1,0] neg_lo:[0,1] neg_hi:[0,1]
	v_pk_add_f32 v[112:113], v[112:113], v[234:235] op_sel_hi:[1,0] neg_lo:[0,1] neg_hi:[0,1]
	v_pk_add_f32 v[106:107], v[106:107], v[234:235] op_sel_hi:[1,0] neg_lo:[0,1] neg_hi:[0,1]
	v_pk_add_f32 v[104:105], v[104:105], v[234:235] op_sel_hi:[1,0] neg_lo:[0,1] neg_hi:[0,1]
	v_pk_add_f32 v[122:123], v[122:123], v[234:235] op_sel_hi:[1,0] neg_lo:[0,1] neg_hi:[0,1]
	v_pk_add_f32 v[120:121], v[120:121], v[234:235] op_sel_hi:[1,0] neg_lo:[0,1] neg_hi:[0,1]
	v_exp_f32_e32 v96, v96
	v_exp_f32_e32 v97, v97
	v_exp_f32_e32 v98, v98
	v_exp_f32_e32 v99, v99
	v_exp_f32_e32 v100, v100
	v_exp_f32_e32 v101, v101
	v_exp_f32_e32 v102, v102
	v_exp_f32_e32 v103, v103
	v_exp_f32_e32 v112, v112
	v_exp_f32_e32 v113, v113
	v_exp_f32_e32 v114, v114
	v_exp_f32_e32 v115, v115
	v_exp_f32_e32 v116, v116
	v_exp_f32_e32 v117, v117
	v_exp_f32_e32 v118, v118
	v_exp_f32_e32 v119, v119
	v_pk_add_f32 v[110:111], v[110:111], v[234:235] op_sel_hi:[1,0] neg_lo:[0,1] neg_hi:[0,1]
	v_pk_add_f32 v[108:109], v[108:109], v[234:235] op_sel_hi:[1,0] neg_lo:[0,1] neg_hi:[0,1]
	v_pk_add_f32 v[126:127], v[126:127], v[234:235] op_sel_hi:[1,0] neg_lo:[0,1] neg_hi:[0,1]
	v_pk_add_f32 v[124:125], v[124:125], v[234:235] op_sel_hi:[1,0] neg_lo:[0,1] neg_hi:[0,1]
	v_exp_f32_e32 v104, v104
	v_exp_f32_e32 v105, v105
	v_exp_f32_e32 v106, v106
	v_exp_f32_e32 v107, v107
	v_exp_f32_e32 v120, v120
	v_exp_f32_e32 v122, v122
	v_exp_f32_e32 v123, v123
	v_exp_f32_e32 v121, v121
	v_exp_f32_e32 v108, v108
	v_exp_f32_e32 v109, v109
	v_exp_f32_e32 v110, v110
	v_exp_f32_e32 v111, v111
	v_exp_f32_e32 v124, v124
	v_exp_f32_e32 v125, v125
	v_exp_f32_e32 v126, v126
	v_exp_f32_e32 v127, v127
	v_pk_add_f32 v[226:227], v[100:101], v[116:117]
	v_pk_add_f32 v[236:237], v[96:97], v[112:113]
	v_pk_add_f32 v[238:239], v[102:103], v[118:119]
	v_pk_add_f32 v[240:241], v[98:99], v[114:115]
	v_pk_add_f32 v[222:223], v[106:107], v[122:123]
	v_pk_add_f32 v[224:225], v[104:105], v[120:121]
	v_pk_add_f32 v[238:239], v[240:241], v[238:239]
	v_pk_add_f32 v[226:227], v[236:237], v[226:227]
	v_pk_add_f32 v[162:163], v[108:109], v[124:125]
	v_pk_add_f32 v[164:165], v[110:111], v[126:127]
	v_pk_add_f32 v[224:225], v[224:225], v[226:227]
	v_pk_add_f32 v[222:223], v[222:223], v[238:239]
	v_pk_add_f32 v[162:163], v[162:163], v[224:225]
	v_pk_add_f32 v[164:165], v[164:165], v[222:223]
	v_add_f32_e32 v162, v162, v163
	v_add_f32_e32 v163, v164, v165
	v_add_f32_e32 v162, v162, v163
	v_fmac_f32_e32 v162, v215, v170
	s_setprio 1
	ds_read_b128 v[222:225], v209
	ds_read_b128 v[240:243], v209 offset:4608
	ds_read_b128 v[244:247], v209 offset:9216
	ds_read_b128 v[248:251], v209 offset:13824
	v_cvt_pk_bf16_f32 v236, v96, v97
	v_cvt_pk_bf16_f32 v237, v98, v99
	v_cvt_pk_bf16_f32 v238, v100, v101
	v_cvt_pk_bf16_f32 v239, v102, v103
	s_waitcnt lgkmcnt(3)
	s_nop 0
	v_mfma_f32_32x32x16_bf16 v[48:63], v[222:225], v[236:239], v[48:63]
	ds_read_b128 v[222:225], v209 offset:32
	s_waitcnt lgkmcnt(3)
	v_mfma_f32_32x32x16_bf16 v[32:47], v[240:243], v[236:239], v[32:47]
	ds_read_b128 v[240:243], v209 offset:4640
	s_waitcnt lgkmcnt(3)
	v_mfma_f32_32x32x16_bf16 v[16:31], v[244:247], v[236:239], v[16:31]
	ds_read_b128 v[244:247], v209 offset:9248
	s_waitcnt lgkmcnt(3)
	v_mfma_f32_32x32x16_bf16 v[0:15], v[248:251], v[236:239], v[0:15]
	ds_read_b128 v[248:251], v209 offset:13856
	v_cvt_pk_bf16_f32 v236, v104, v105
	v_cvt_pk_bf16_f32 v237, v106, v107
	v_cvt_pk_bf16_f32 v238, v108, v109
	v_cvt_pk_bf16_f32 v239, v110, v111
	s_waitcnt lgkmcnt(3)
	s_nop 0
	v_mfma_f32_32x32x16_bf16 v[48:63], v[222:225], v[236:239], v[48:63]
	ds_read_b128 v[222:225], v209 offset:64
	s_waitcnt lgkmcnt(3)
	v_mfma_f32_32x32x16_bf16 v[32:47], v[240:243], v[236:239], v[32:47]
	ds_read_b128 v[240:243], v209 offset:4672
	s_waitcnt lgkmcnt(3)
	v_mfma_f32_32x32x16_bf16 v[16:31], v[244:247], v[236:239], v[16:31]
	ds_read_b128 v[244:247], v209 offset:9280
	s_waitcnt lgkmcnt(3)
	v_mfma_f32_32x32x16_bf16 v[0:15], v[248:251], v[236:239], v[0:15]
	ds_read_b128 v[248:251], v209 offset:13888
	v_cvt_pk_bf16_f32 v236, v112, v113
	v_cvt_pk_bf16_f32 v237, v114, v115
	v_cvt_pk_bf16_f32 v238, v116, v117
	v_cvt_pk_bf16_f32 v239, v118, v119
	s_waitcnt lgkmcnt(3)
	s_nop 0
	v_mfma_f32_32x32x16_bf16 v[48:63], v[222:225], v[236:239], v[48:63]
	ds_read_b128 v[222:225], v209 offset:96
	s_waitcnt lgkmcnt(3)
	v_mfma_f32_32x32x16_bf16 v[32:47], v[240:243], v[236:239], v[32:47]
	ds_read_b128 v[240:243], v209 offset:4704
	s_waitcnt lgkmcnt(3)
	v_mfma_f32_32x32x16_bf16 v[16:31], v[244:247], v[236:239], v[16:31]
	ds_read_b128 v[244:247], v209 offset:9312
	s_waitcnt lgkmcnt(3)
	v_mfma_f32_32x32x16_bf16 v[0:15], v[248:251], v[236:239], v[0:15]
	ds_read_b128 v[248:251], v209 offset:13920
	v_cvt_pk_bf16_f32 v236, v120, v121
	v_cvt_pk_bf16_f32 v237, v122, v123
	v_cvt_pk_bf16_f32 v238, v124, v125
	v_cvt_pk_bf16_f32 v239, v126, v127
	s_waitcnt lgkmcnt(3)
	s_nop 0
	v_mfma_f32_32x32x16_bf16 v[48:63], v[222:225], v[236:239], v[48:63]
	s_waitcnt lgkmcnt(2)
	v_mfma_f32_32x32x16_bf16 v[32:47], v[240:243], v[236:239], v[32:47]
	s_waitcnt lgkmcnt(1)
	v_mfma_f32_32x32x16_bf16 v[16:31], v[244:247], v[236:239], v[16:31]
	s_waitcnt lgkmcnt(0)
	v_mfma_f32_32x32x16_bf16 v[0:15], v[248:251], v[236:239], v[0:15]
	s_setprio 0
	v_mov_b32_e32 v170, v234
	v_mov_b32_e32 v215, v162

.LBB0_212:
	v_pk_add_f32 v[70:71], v[70:71], v[234:235] op_sel_hi:[1,0] neg_lo:[0,1] neg_hi:[0,1]
	v_pk_add_f32 v[68:69], v[68:69], v[234:235] op_sel_hi:[1,0] neg_lo:[0,1] neg_hi:[0,1]
	v_pk_add_f32 v[66:67], v[66:67], v[234:235] op_sel_hi:[1,0] neg_lo:[0,1] neg_hi:[0,1]
	v_pk_add_f32 v[64:65], v[64:65], v[234:235] op_sel_hi:[1,0] neg_lo:[0,1] neg_hi:[0,1]
	v_pk_add_f32 v[86:87], v[86:87], v[234:235] op_sel_hi:[1,0] neg_lo:[0,1] neg_hi:[0,1]
	v_pk_add_f32 v[84:85], v[84:85], v[234:235] op_sel_hi:[1,0] neg_lo:[0,1] neg_hi:[0,1]
	v_pk_add_f32 v[82:83], v[82:83], v[234:235] op_sel_hi:[1,0] neg_lo:[0,1] neg_hi:[0,1]
	v_pk_add_f32 v[80:81], v[80:81], v[234:235] op_sel_hi:[1,0] neg_lo:[0,1] neg_hi:[0,1]
	v_pk_add_f32 v[74:75], v[74:75], v[234:235] op_sel_hi:[1,0] neg_lo:[0,1] neg_hi:[0,1]
	v_pk_add_f32 v[72:73], v[72:73], v[234:235] op_sel_hi:[1,0] neg_lo:[0,1] neg_hi:[0,1]
	v_pk_add_f32 v[90:91], v[90:91], v[234:235] op_sel_hi:[1,0] neg_lo:[0,1] neg_hi:[0,1]
	v_pk_add_f32 v[88:89], v[88:89], v[234:235] op_sel_hi:[1,0] neg_lo:[0,1] neg_hi:[0,1]
	v_exp_f32_e32 v64, v64
	v_exp_f32_e32 v65, v65
	v_exp_f32_e32 v66, v66
	v_exp_f32_e32 v67, v67
	v_exp_f32_e32 v68, v68
	v_exp_f32_e32 v69, v69
	v_exp_f32_e32 v70, v70
	v_exp_f32_e32 v71, v71
	v_exp_f32_e32 v80, v80
	v_exp_f32_e32 v81, v81
	v_exp_f32_e32 v82, v82
	v_exp_f32_e32 v83, v83
	v_exp_f32_e32 v84, v84
	v_exp_f32_e32 v85, v85
	v_exp_f32_e32 v86, v86
	v_exp_f32_e32 v87, v87
	v_pk_add_f32 v[78:79], v[78:79], v[234:235] op_sel_hi:[1,0] neg_lo:[0,1] neg_hi:[0,1]
	v_pk_add_f32 v[76:77], v[76:77], v[234:235] op_sel_hi:[1,0] neg_lo:[0,1] neg_hi:[0,1]
	v_pk_add_f32 v[94:95], v[94:95], v[234:235] op_sel_hi:[1,0] neg_lo:[0,1] neg_hi:[0,1]
	v_pk_add_f32 v[92:93], v[92:93], v[234:235] op_sel_hi:[1,0] neg_lo:[0,1] neg_hi:[0,1]
	v_exp_f32_e32 v72, v72
	v_exp_f32_e32 v73, v73
	v_exp_f32_e32 v74, v74
	v_exp_f32_e32 v75, v75
	v_exp_f32_e32 v88, v88
	v_exp_f32_e32 v90, v90
	v_exp_f32_e32 v91, v91
	v_exp_f32_e32 v89, v89
	v_exp_f32_e32 v76, v76
	v_exp_f32_e32 v77, v77
	v_exp_f32_e32 v78, v78
	v_exp_f32_e32 v79, v79
	v_exp_f32_e32 v92, v92
	v_exp_f32_e32 v93, v93
	v_exp_f32_e32 v94, v94
	v_exp_f32_e32 v95, v95
	v_pk_add_f32 v[226:227], v[68:69], v[84:85]
	v_pk_add_f32 v[236:237], v[64:65], v[80:81]
	v_pk_add_f32 v[238:239], v[70:71], v[86:87]
	v_pk_add_f32 v[240:241], v[66:67], v[82:83]
	v_pk_add_f32 v[222:223], v[74:75], v[90:91]
	v_pk_add_f32 v[224:225], v[72:73], v[88:89]
	v_pk_add_f32 v[238:239], v[240:241], v[238:239]
	v_pk_add_f32 v[226:227], v[236:237], v[226:227]
	v_pk_add_f32 v[162:163], v[76:77], v[92:93]
	v_pk_add_f32 v[164:165], v[78:79], v[94:95]
	v_pk_add_f32 v[224:225], v[224:225], v[226:227]
	v_pk_add_f32 v[222:223], v[222:223], v[238:239]
	v_pk_add_f32 v[162:163], v[162:163], v[224:225]
	v_pk_add_f32 v[164:165], v[164:165], v[222:223]
	v_add_f32_e32 v162, v162, v163
	v_add_f32_e32 v163, v164, v165
	v_add_f32_e32 v162, v162, v163
	v_fmac_f32_e32 v162, v215, v170
	s_setprio 1
	v_add_u32_e32 v163, v202, v169
	ds_read_b128 v[222:225], v163 offset:52224
	ds_read_b128 v[240:243], v163 offset:56832
	ds_read_b128 v[244:247], v163 offset:61440
	ds_read_b128 v[248:251], v207 offset:52224
	v_cvt_pk_bf16_f32 v236, v64, v65
	v_cvt_pk_bf16_f32 v237, v66, v67
	v_cvt_pk_bf16_f32 v238, v68, v69
	v_cvt_pk_bf16_f32 v239, v70, v71
	s_waitcnt lgkmcnt(3)
	s_nop 0
	v_mfma_f32_32x32x16_bf16 v[48:63], v[222:225], v[236:239], v[48:63]
	ds_read_b128 v[222:225], v163 offset:52256
	s_waitcnt lgkmcnt(3)
	v_mfma_f32_32x32x16_bf16 v[32:47], v[240:243], v[236:239], v[32:47]
	ds_read_b128 v[240:243], v163 offset:56864
	s_waitcnt lgkmcnt(3)
	v_mfma_f32_32x32x16_bf16 v[16:31], v[244:247], v[236:239], v[16:31]
	ds_read_b128 v[244:247], v163 offset:61472
	s_waitcnt lgkmcnt(3)
	v_mfma_f32_32x32x16_bf16 v[0:15], v[248:251], v[236:239], v[0:15]
	ds_read_b128 v[248:251], v207 offset:52256
	v_cvt_pk_bf16_f32 v236, v72, v73
	v_cvt_pk_bf16_f32 v237, v74, v75
	v_cvt_pk_bf16_f32 v238, v76, v77
	v_cvt_pk_bf16_f32 v239, v78, v79
	s_waitcnt lgkmcnt(3)
	s_nop 0
	v_mfma_f32_32x32x16_bf16 v[48:63], v[222:225], v[236:239], v[48:63]
	ds_read_b128 v[222:225], v163 offset:52288
	s_waitcnt lgkmcnt(3)
	v_mfma_f32_32x32x16_bf16 v[32:47], v[240:243], v[236:239], v[32:47]
	ds_read_b128 v[240:243], v163 offset:56896
	s_waitcnt lgkmcnt(3)
	v_mfma_f32_32x32x16_bf16 v[16:31], v[244:247], v[236:239], v[16:31]
	ds_read_b128 v[244:247], v163 offset:61504
	s_waitcnt lgkmcnt(3)
	v_mfma_f32_32x32x16_bf16 v[0:15], v[248:251], v[236:239], v[0:15]
	ds_read_b128 v[248:251], v207 offset:52288
	v_cvt_pk_bf16_f32 v236, v80, v81
	v_cvt_pk_bf16_f32 v237, v82, v83
	v_cvt_pk_bf16_f32 v238, v84, v85
	v_cvt_pk_bf16_f32 v239, v86, v87
	s_waitcnt lgkmcnt(3)
	s_nop 0
	v_mfma_f32_32x32x16_bf16 v[48:63], v[222:225], v[236:239], v[48:63]
	ds_read_b128 v[222:225], v163 offset:52320
	s_waitcnt lgkmcnt(3)
	v_mfma_f32_32x32x16_bf16 v[32:47], v[240:243], v[236:239], v[32:47]
	ds_read_b128 v[240:243], v163 offset:56928
	s_waitcnt lgkmcnt(3)
	v_mfma_f32_32x32x16_bf16 v[16:31], v[244:247], v[236:239], v[16:31]
	ds_read_b128 v[244:247], v163 offset:61536
	s_waitcnt lgkmcnt(3)
	v_mfma_f32_32x32x16_bf16 v[0:15], v[248:251], v[236:239], v[0:15]
	ds_read_b128 v[248:251], v207 offset:52320
	v_cvt_pk_bf16_f32 v236, v88, v89
	v_cvt_pk_bf16_f32 v237, v90, v91
	v_cvt_pk_bf16_f32 v238, v92, v93
	v_cvt_pk_bf16_f32 v239, v94, v95
	s_waitcnt lgkmcnt(3)
	s_nop 0
	v_mfma_f32_32x32x16_bf16 v[48:63], v[222:225], v[236:239], v[48:63]
	s_waitcnt lgkmcnt(2)
	v_mfma_f32_32x32x16_bf16 v[32:47], v[240:243], v[236:239], v[32:47]
	s_waitcnt lgkmcnt(1)
	v_mfma_f32_32x32x16_bf16 v[16:31], v[244:247], v[236:239], v[16:31]
	s_waitcnt lgkmcnt(0)
	v_mfma_f32_32x32x16_bf16 v[0:15], v[248:251], v[236:239], v[0:15]
	s_setprio 0
	v_mov_b32_e32 v170, v234
	v_mov_b32_e32 v215, v162
